# stack20 + required wait states between v_cmp and v_cndmask in the placement-check code (hazard table row 18); no functional change
# speedup vs baseline: 1.0023x; 1.0011x over previous
; #define LAS __attribute__((address_space(3)))
; __device__ __forceinline__ unsigned xb_ld(unsigned* p)              { return __hip_atomic_load(p, __ATOMIC_RELAXED, __HIP_MEMORY_SCOPE_AGENT); }
; __device__ __forceinline__ unsigned xb_add(unsigned* p, unsigned v) { return __hip_atomic_fetch_add(p, v, __ATOMIC_RELAXED, __HIP_MEMORY_SCOPE_AGENT); }
; __device__ __forceinline__ unsigned xb_xcc_id() { return (unsigned)__builtin_amdgcn_s_getreg((3 << 11) | 20) & 0xFu; }
; __device__ __forceinline__ XcdBarrier xcd_barrier_post(unsigned* bar, volatile LAS unsigned* st) {
;     XcdBarrier b; b.bar = bar; b.x = xb_xcc_id(); b.st = st;
;     if (threadIdx.x == 0) (void)xb_add(&bar[XB_XCNT(b.x)], 1u);
;     return b;
; }
; __device__ __forceinline__ void xcd_barrier_complete(unsigned* bar, unsigned x, unsigned& nloc, unsigned& nx) {
;     const unsigned G = gridDim.x * gridDim.y * gridDim.z;
;     unsigned sum, cnt, mine, sp = 0u;
;     for (;;) {
;         sum = 0u; cnt = 0u; mine = 0u;
; #pragma unroll
;         for (unsigned j = 0; j < 16; ++j) { const unsigned c = xb_ld(&bar[XB_XCNT(j)]); sum += c; cnt += (c > 0u) ? 1u : 0u; mine = (j == x) ? c : mine; }
;         if (sum == G) break;
;         __builtin_amdgcn_s_sleep(1);
;         if ((++sp & 255u) == 0u) { if (xb_ld(&bar[XB_TMO])) break; if (sp > XB_SPIN_CAP) { atomicAdd(&bar[XB_TMO], 1u); break; } }
;     }
;     nloc = mine > 0u ? mine : 1u; nx = cnt > 0u ? cnt : 1u;
; }
.Lxb_p0_done:
	v_mov_b32_e32 v9, 0x3600
	global_load_dwordx4 v[10:13], v9, s[98:99] sc1
	global_load_dwordx4 v[14:17], v9, s[98:99] offset:16 sc1
	s_waitcnt vmcnt(0)
	v_or_b32_e32 v9, v10, v11
	v_or3_b32 v9, v9, v12, v13
	v_or3_b32 v9, v9, v14, v15
	v_or3_b32 v9, v9, v16, v17
	v_bcnt_u32_b32 v9, v9, 0
	v_bcnt_u32_b32 v10, v10, 0
	v_bcnt_u32_b32 v10, v11, v10
	v_bcnt_u32_b32 v10, v12, v10
	v_bcnt_u32_b32 v10, v13, v10
	v_bcnt_u32_b32 v10, v14, v10
	v_bcnt_u32_b32 v10, v15, v10
	v_bcnt_u32_b32 v10, v16, v10
	v_bcnt_u32_b32 v10, v17, v10
	v_cmp_ne_u32_e32 vcc, 8, v9
	s_nop 1
	v_cndmask_b32_e64 v9, 0, 1, vcc
	v_cmp_ne_u32_e32 vcc, 8, v10
	s_nop 1
	v_cndmask_b32_e64 v10, 0, 1, vcc
	v_cmp_ne_u32_e32 vcc, 8, v1
	s_nop 1
	v_cndmask_b32_e64 v11, 0, 1, vcc
	v_or3_b32 v9, v9, v10, v11
	v_mov_b32_e32 v10, 0x21ff8
	ds_write_b32 v10, v9
